# od_in epilogue: eight per-row-group ssq loads issued together (later groups no longer wait on vmcnt behind their own stores)
# speedup vs baseline: 1.0035x; 1.0035x over previous
.LBB0_928:
	v_lshl_add_u32 v134, s13, 8, v145
	v_ashrrev_i32_e32 v135, 31, v134
	v_lshl_add_u64 v[136:137], v[134:135], 2, s[36:37]
	global_load_dword v138, v[136:137], off
	global_load_dword v160, v[136:137], off offset:64
	global_load_dword v161, v[136:137], off offset:128
	global_load_dword v162, v[136:137], off offset:192
	global_load_dword v163, v[136:137], off offset:512
	global_load_dword v164, v[136:137], off offset:576
	global_load_dword v165, v[136:137], off offset:640
	global_load_dword v166, v[136:137], off offset:704
	s_mov_b32 s2, 0x800000
	s_cmp_lt_i32 s12, 4
	s_movk_i32 s0, 0xf800
	s_cselect_b64 s[10:11], -1, 0
	s_cmp_gt_i32 s12, 3
	s_mov_b32 s1, -1
	s_waitcnt vmcnt(0)
	v_fmamk_f32 v138, v138, 0x3a800000, v227
	v_mul_f32_e32 v139, 0x4b800000, v138
	v_cmp_gt_f32_e32 vcc, s2, v138
	s_nop 1
	v_cndmask_b32_e32 v138, v138, v139, vcc
	v_rsq_f32_e32 v138, v138
	s_nop 0
	v_mul_f32_e32 v139, 0x45800000, v138
	v_cndmask_b32_e32 v138, v138, v139, vcc
	v_pk_mul_f32 v[126:127], v[126:127], v[138:139] op_sel_hi:[1,0]
	v_pk_mul_f32 v[124:125], v[124:125], v[138:139] op_sel_hi:[1,0]
	v_pk_mul_f32 v[140:141], v[122:123], v[138:139] op_sel_hi:[1,0]
	v_pk_mul_f32 v[142:143], v[120:121], v[138:139] op_sel_hi:[1,0]
	s_cbranch_scc1 .LBB0_930
	v_mul_f32_e32 v121, 0x3d372713, v142
	v_mul_f32_e32 v121, v142, v121
	v_fma_f32 v121, v142, v121, v142
	v_mul_f32_e32 v121, 0x3f4c422a, v121
	v_add_f32_e32 v121, v121, v121
	v_mul_f32_e32 v121, 0xbfb8aa3b, v121
	v_exp_f32_e32 v121, v121
	v_mov_b32_e32 v123, v125
	v_mov_b32_e32 v139, v143
	v_mul_f32_e32 v120, 0x3d372713, v124
	v_add_f32_e32 v121, 1.0, v121
	v_rcp_f32_e32 v122, v121
	v_mul_f32_e32 v121, 0x3d372713, v125
	v_mul_f32_e32 v121, v125, v121
	v_fmac_f32_e32 v123, v123, v121
	v_mul_f32_e32 v121, 0x3f4c422a, v123
	v_mul_f32_e32 v123, 0x3d372713, v143
	v_mul_f32_e32 v123, v143, v123
	v_fmac_f32_e32 v139, v139, v123
	v_mul_f32_e32 v123, 0x3f4c422a, v139
	v_mul_f32_e32 v139, 0x3d372713, v126
	v_mul_f32_e32 v139, v126, v139
	v_fma_f32 v139, v126, v139, v126
	v_mul_f32_e32 v139, 0x3f4c422a, v139
	v_add_f32_e32 v139, v139, v139
	v_mul_f32_e32 v139, 0xbfb8aa3b, v139
	v_exp_f32_e32 v139, v139
	v_mul_f32_e32 v120, v124, v120
	v_fma_f32 v120, v124, v120, v124
	v_mul_f32_e32 v120, 0x3f4c422a, v120
	v_add_f32_e32 v139, 1.0, v139
	v_add_f32_e32 v120, v120, v120
	v_add_f32_e32 v121, v121, v121
	v_rcp_f32_e32 v150, v139
	v_mul_f32_e32 v139, 0x3d372713, v140
	v_mul_f32_e32 v120, 0xbfb8aa3b, v120
	v_mul_f32_e32 v121, 0xbfb8aa3b, v121
	v_mul_f32_e32 v139, v140, v139
	v_exp_f32_e32 v120, v120
	v_exp_f32_e32 v121, v121
	v_fma_f32 v139, v140, v139, v140
	v_mul_f32_e32 v139, 0x3f4c422a, v139
	v_add_f32_e32 v139, v139, v139
	v_mul_f32_e32 v139, 0xbfb8aa3b, v139
	v_add_f32_e32 v120, 1.0, v120
	v_add_f32_e32 v121, 1.0, v121
	v_exp_f32_e32 v139, v139
	v_rcp_f32_e32 v120, v120
	v_rcp_f32_e32 v121, v121
	v_add_f32_e32 v123, v123, v123
	v_add_f32_e32 v139, 1.0, v139
	v_rcp_f32_e32 v152, v139
	v_mul_f32_e32 v139, 0x3d372713, v127
	v_pk_mul_f32 v[124:125], v[124:125], v[120:121]
	v_mul_f32_e32 v120, 0x3d372713, v141
	v_mul_f32_e32 v139, v127, v139
	v_mul_f32_e32 v120, v141, v120
	v_fma_f32 v139, v127, v139, v127
	v_fma_f32 v120, v141, v120, v141
	v_mul_f32_e32 v139, 0x3f4c422a, v139
	v_mul_f32_e32 v120, 0x3f4c422a, v120
	v_add_f32_e32 v139, v139, v139
	v_add_f32_e32 v120, v120, v120
	v_mul_f32_e32 v123, 0xbfb8aa3b, v123
	v_mul_f32_e32 v139, 0xbfb8aa3b, v139
	v_mul_f32_e32 v120, 0xbfb8aa3b, v120
	v_exp_f32_e32 v123, v123
	v_exp_f32_e32 v139, v139
	v_exp_f32_e32 v120, v120
	v_add_f32_e32 v123, 1.0, v123
	v_add_f32_e32 v139, 1.0, v139
	v_add_f32_e32 v120, 1.0, v120
	v_rcp_f32_e32 v123, v123
	v_rcp_f32_e32 v151, v139
	v_rcp_f32_e32 v153, v120
	v_pk_mul_f32 v[142:143], v[142:143], v[122:123]
	v_pk_mul_f32 v[126:127], v[126:127], v[150:151]
	v_pk_mul_f32 v[140:141], v[140:141], v[152:153]

.LBB0_932:
	v_cvt_pk_bf16_f32 v116, v116, v117
	v_cvt_pk_bf16_f32 v117, v118, v119
	v_cvt_pk_bf16_f32 v119, v114, v115
	v_or_b32_e32 v114, 16, v134
	v_cvt_pk_bf16_f32 v118, v112, v113
	v_ashrrev_i32_e32 v115, 31, v114
	global_store_dwordx4 v[122:123], v[116:119], off offset:256
	v_mov_b32_e32 v112, v160
	s_and_b64 vcc, exec, s[12:13]
	v_fmamk_f32 v112, v112, 0x3a800000, v227
	v_mul_f32_e32 v113, 0x4b800000, v112
	v_cmp_gt_f32_e64 s[16:17], s2, v112
	s_nop 1
	v_cndmask_b32_e64 v112, v112, v113, s[16:17]
	v_rsq_f32_e32 v112, v112
	s_nop 0
	v_mul_f32_e32 v113, 0x45800000, v112
	v_cndmask_b32_e64 v112, v112, v113, s[16:17]
	v_pk_mul_f32 v[110:111], v[110:111], v[112:113] op_sel_hi:[1,0]
	v_pk_mul_f32 v[116:117], v[108:109], v[112:113] op_sel_hi:[1,0]
	v_pk_mul_f32 v[106:107], v[106:107], v[112:113] op_sel_hi:[1,0]
	v_pk_mul_f32 v[108:109], v[104:105], v[112:113] op_sel_hi:[1,0]
	s_cbranch_vccnz .LBB0_934
	v_mul_f32_e32 v105, 0x3d372713, v108
	v_mul_f32_e32 v105, v108, v105
	v_fma_f32 v105, v108, v105, v108
	v_mul_f32_e32 v105, 0x3f4c422a, v105
	v_add_f32_e32 v105, v105, v105
	v_mul_f32_e32 v105, 0xbfb8aa3b, v105
	v_exp_f32_e32 v105, v105
	v_mov_b32_e32 v113, v117
	v_mov_b32_e32 v119, v109
	v_mul_f32_e32 v104, 0x3d372713, v116
	v_add_f32_e32 v105, 1.0, v105
	v_rcp_f32_e32 v118, v105
	v_mul_f32_e32 v105, 0x3d372713, v117
	v_mul_f32_e32 v105, v117, v105
	v_fmac_f32_e32 v113, v113, v105
	v_mul_f32_e32 v105, 0x3f4c422a, v113
	v_mul_f32_e32 v113, 0x3d372713, v109
	v_mul_f32_e32 v113, v109, v113
	v_fmac_f32_e32 v119, v119, v113
	v_mul_f32_e32 v113, 0x3f4c422a, v119
	v_add_f32_e32 v113, v113, v113
	v_mul_f32_e32 v113, 0xbfb8aa3b, v113
	v_exp_f32_e32 v113, v113
	v_mul_f32_e32 v104, v116, v104
	v_fma_f32 v104, v116, v104, v116
	v_mul_f32_e32 v104, 0x3f4c422a, v104
	v_add_f32_e32 v113, 1.0, v113
	v_rcp_f32_e32 v119, v113
	v_mul_f32_e32 v113, 0x3d372713, v110
	v_mul_f32_e32 v113, v110, v113
	v_fma_f32 v113, v110, v113, v110
	v_mul_f32_e32 v113, 0x3f4c422a, v113
	v_add_f32_e32 v113, v113, v113
	v_mul_f32_e32 v113, 0xbfb8aa3b, v113
	v_exp_f32_e32 v113, v113
	v_add_f32_e32 v104, v104, v104
	v_add_f32_e32 v105, v105, v105
	v_mul_f32_e32 v104, 0xbfb8aa3b, v104
	v_add_f32_e32 v113, 1.0, v113
	v_rcp_f32_e32 v122, v113
	v_mul_f32_e32 v113, 0x3d372713, v106
	v_mul_f32_e32 v105, 0xbfb8aa3b, v105
	v_mul_f32_e32 v113, v106, v113
	v_exp_f32_e32 v104, v104
	v_exp_f32_e32 v105, v105
	v_fma_f32 v113, v106, v113, v106
	v_mul_f32_e32 v113, 0x3f4c422a, v113
	v_add_f32_e32 v113, v113, v113
	v_mul_f32_e32 v113, 0xbfb8aa3b, v113
	v_add_f32_e32 v104, 1.0, v104
	v_add_f32_e32 v105, 1.0, v105
	v_exp_f32_e32 v113, v113
	v_rcp_f32_e32 v104, v104
	v_rcp_f32_e32 v105, v105
	v_pk_mul_f32 v[108:109], v[108:109], v[118:119]
	v_add_f32_e32 v113, 1.0, v113
	v_rcp_f32_e32 v124, v113
	v_mul_f32_e32 v113, 0x3d372713, v111
	v_pk_mul_f32 v[116:117], v[116:117], v[104:105]
	v_mul_f32_e32 v104, 0x3d372713, v107
	v_mul_f32_e32 v113, v111, v113
	v_mul_f32_e32 v104, v107, v104
	v_fma_f32 v113, v111, v113, v111
	v_fma_f32 v104, v107, v104, v107
	v_mul_f32_e32 v113, 0x3f4c422a, v113
	v_mul_f32_e32 v104, 0x3f4c422a, v104
	v_add_f32_e32 v113, v113, v113
	v_add_f32_e32 v104, v104, v104
	v_mul_f32_e32 v113, 0xbfb8aa3b, v113
	v_mul_f32_e32 v104, 0xbfb8aa3b, v104
	v_exp_f32_e32 v113, v113
	v_exp_f32_e32 v104, v104
	v_add_f32_e32 v113, 1.0, v113
	v_add_f32_e32 v104, 1.0, v104
	v_rcp_f32_e32 v123, v113
	v_rcp_f32_e32 v125, v104
	v_pk_mul_f32 v[110:111], v[110:111], v[122:123]
	v_pk_mul_f32 v[106:107], v[106:107], v[124:125]

.LBB0_936:
	v_cvt_pk_bf16_f32 v100, v100, v101
	v_cvt_pk_bf16_f32 v101, v102, v103
	v_cvt_pk_bf16_f32 v103, v98, v99
	v_or_b32_e32 v98, 32, v134
	v_cvt_pk_bf16_f32 v102, v96, v97
	v_ashrrev_i32_e32 v99, 31, v98
	global_store_dwordx4 v[104:105], v[100:103], off offset:256
	v_mov_b32_e32 v96, v161
	s_and_b64 vcc, exec, s[12:13]
	v_fmamk_f32 v96, v96, 0x3a800000, v227
	v_mul_f32_e32 v97, 0x4b800000, v96
	v_cmp_gt_f32_e64 s[16:17], s2, v96
	s_nop 1
	v_cndmask_b32_e64 v96, v96, v97, s[16:17]
	v_rsq_f32_e32 v96, v96
	s_nop 0
	v_mul_f32_e32 v97, 0x45800000, v96
	v_cndmask_b32_e64 v96, v96, v97, s[16:17]
	v_pk_mul_f32 v[94:95], v[94:95], v[96:97] op_sel_hi:[1,0]
	v_pk_mul_f32 v[100:101], v[92:93], v[96:97] op_sel_hi:[1,0]
	v_pk_mul_f32 v[90:91], v[90:91], v[96:97] op_sel_hi:[1,0]
	v_pk_mul_f32 v[92:93], v[88:89], v[96:97] op_sel_hi:[1,0]
	s_cbranch_vccnz .LBB0_938
	v_mul_f32_e32 v89, 0x3d372713, v92
	v_mul_f32_e32 v89, v92, v89
	v_fma_f32 v89, v92, v89, v92
	v_mul_f32_e32 v89, 0x3f4c422a, v89
	v_add_f32_e32 v89, v89, v89
	v_mul_f32_e32 v89, 0xbfb8aa3b, v89
	v_exp_f32_e32 v89, v89
	v_mov_b32_e32 v97, v101
	v_mov_b32_e32 v103, v93
	v_mul_f32_e32 v88, 0x3d372713, v100
	v_add_f32_e32 v89, 1.0, v89
	v_rcp_f32_e32 v102, v89
	v_mul_f32_e32 v89, 0x3d372713, v101
	v_mul_f32_e32 v89, v101, v89
	v_fmac_f32_e32 v97, v97, v89
	v_mul_f32_e32 v89, 0x3f4c422a, v97
	v_mul_f32_e32 v97, 0x3d372713, v93
	v_mul_f32_e32 v97, v93, v97
	v_fmac_f32_e32 v103, v103, v97
	v_mul_f32_e32 v97, 0x3f4c422a, v103
	v_add_f32_e32 v97, v97, v97
	v_mul_f32_e32 v97, 0xbfb8aa3b, v97
	v_exp_f32_e32 v97, v97
	v_mul_f32_e32 v88, v100, v88
	v_fma_f32 v88, v100, v88, v100
	v_mul_f32_e32 v88, 0x3f4c422a, v88
	v_add_f32_e32 v97, 1.0, v97
	v_rcp_f32_e32 v103, v97
	v_mul_f32_e32 v97, 0x3d372713, v94
	v_mul_f32_e32 v97, v94, v97
	v_fma_f32 v97, v94, v97, v94
	v_mul_f32_e32 v97, 0x3f4c422a, v97
	v_add_f32_e32 v97, v97, v97
	v_mul_f32_e32 v97, 0xbfb8aa3b, v97
	v_exp_f32_e32 v97, v97
	v_add_f32_e32 v88, v88, v88
	v_add_f32_e32 v89, v89, v89
	v_mul_f32_e32 v88, 0xbfb8aa3b, v88
	v_add_f32_e32 v97, 1.0, v97
	v_rcp_f32_e32 v104, v97
	v_mul_f32_e32 v97, 0x3d372713, v90
	v_mul_f32_e32 v89, 0xbfb8aa3b, v89
	v_mul_f32_e32 v97, v90, v97
	v_exp_f32_e32 v88, v88
	v_exp_f32_e32 v89, v89
	v_fma_f32 v97, v90, v97, v90
	v_mul_f32_e32 v97, 0x3f4c422a, v97
	v_add_f32_e32 v97, v97, v97
	v_mul_f32_e32 v97, 0xbfb8aa3b, v97
	v_add_f32_e32 v88, 1.0, v88
	v_add_f32_e32 v89, 1.0, v89
	v_exp_f32_e32 v97, v97
	v_rcp_f32_e32 v88, v88
	v_rcp_f32_e32 v89, v89
	v_pk_mul_f32 v[92:93], v[92:93], v[102:103]
	v_add_f32_e32 v97, 1.0, v97
	v_rcp_f32_e32 v106, v97
	v_mul_f32_e32 v97, 0x3d372713, v95
	v_pk_mul_f32 v[100:101], v[100:101], v[88:89]
	v_mul_f32_e32 v88, 0x3d372713, v91
	v_mul_f32_e32 v97, v95, v97
	v_mul_f32_e32 v88, v91, v88
	v_fma_f32 v97, v95, v97, v95
	v_fma_f32 v88, v91, v88, v91
	v_mul_f32_e32 v97, 0x3f4c422a, v97
	v_mul_f32_e32 v88, 0x3f4c422a, v88
	v_add_f32_e32 v97, v97, v97
	v_add_f32_e32 v88, v88, v88
	v_mul_f32_e32 v97, 0xbfb8aa3b, v97
	v_mul_f32_e32 v88, 0xbfb8aa3b, v88
	v_exp_f32_e32 v97, v97
	v_exp_f32_e32 v88, v88
	v_add_f32_e32 v97, 1.0, v97
	v_add_f32_e32 v88, 1.0, v88
	v_rcp_f32_e32 v105, v97
	v_rcp_f32_e32 v107, v88
	v_pk_mul_f32 v[94:95], v[94:95], v[104:105]
	v_pk_mul_f32 v[90:91], v[90:91], v[106:107]

.LBB0_940:
	v_cvt_pk_bf16_f32 v84, v84, v85
	v_cvt_pk_bf16_f32 v85, v86, v87
	v_cvt_pk_bf16_f32 v87, v82, v83
	v_or_b32_e32 v82, 48, v134
	v_cvt_pk_bf16_f32 v86, v80, v81
	v_ashrrev_i32_e32 v83, 31, v82
	global_store_dwordx4 v[88:89], v[84:87], off offset:256
	v_mov_b32_e32 v80, v162
	s_and_b64 vcc, exec, s[12:13]
	v_fmamk_f32 v80, v80, 0x3a800000, v227
	v_mul_f32_e32 v81, 0x4b800000, v80
	v_cmp_gt_f32_e64 s[16:17], s2, v80
	s_nop 1
	v_cndmask_b32_e64 v80, v80, v81, s[16:17]
	v_rsq_f32_e32 v80, v80
	s_nop 0
	v_mul_f32_e32 v81, 0x45800000, v80
	v_cndmask_b32_e64 v80, v80, v81, s[16:17]
	v_pk_mul_f32 v[78:79], v[78:79], v[80:81] op_sel_hi:[1,0]
	v_pk_mul_f32 v[84:85], v[76:77], v[80:81] op_sel_hi:[1,0]
	v_pk_mul_f32 v[74:75], v[74:75], v[80:81] op_sel_hi:[1,0]
	v_pk_mul_f32 v[76:77], v[72:73], v[80:81] op_sel_hi:[1,0]
	s_cbranch_vccnz .LBB0_942
	v_mul_f32_e32 v73, 0x3d372713, v76
	v_mul_f32_e32 v73, v76, v73
	v_fma_f32 v73, v76, v73, v76
	v_mul_f32_e32 v73, 0x3f4c422a, v73
	v_add_f32_e32 v73, v73, v73
	v_mul_f32_e32 v73, 0xbfb8aa3b, v73
	v_exp_f32_e32 v73, v73
	v_mov_b32_e32 v81, v85
	v_mov_b32_e32 v87, v77
	v_mul_f32_e32 v72, 0x3d372713, v84
	v_add_f32_e32 v73, 1.0, v73
	v_rcp_f32_e32 v86, v73
	v_mul_f32_e32 v73, 0x3d372713, v85
	v_mul_f32_e32 v73, v85, v73
	v_fmac_f32_e32 v81, v81, v73
	v_mul_f32_e32 v73, 0x3f4c422a, v81
	v_mul_f32_e32 v81, 0x3d372713, v77
	v_mul_f32_e32 v81, v77, v81
	v_fmac_f32_e32 v87, v87, v81
	v_mul_f32_e32 v81, 0x3f4c422a, v87
	v_add_f32_e32 v81, v81, v81
	v_mul_f32_e32 v81, 0xbfb8aa3b, v81
	v_exp_f32_e32 v81, v81
	v_mul_f32_e32 v72, v84, v72
	v_fma_f32 v72, v84, v72, v84
	v_mul_f32_e32 v72, 0x3f4c422a, v72
	v_add_f32_e32 v81, 1.0, v81
	v_rcp_f32_e32 v87, v81
	v_mul_f32_e32 v81, 0x3d372713, v78
	v_mul_f32_e32 v81, v78, v81
	v_fma_f32 v81, v78, v81, v78
	v_mul_f32_e32 v81, 0x3f4c422a, v81
	v_add_f32_e32 v81, v81, v81
	v_mul_f32_e32 v81, 0xbfb8aa3b, v81
	v_exp_f32_e32 v81, v81
	v_add_f32_e32 v72, v72, v72
	v_add_f32_e32 v73, v73, v73
	v_mul_f32_e32 v72, 0xbfb8aa3b, v72
	v_add_f32_e32 v81, 1.0, v81
	v_rcp_f32_e32 v88, v81
	v_mul_f32_e32 v81, 0x3d372713, v74
	v_mul_f32_e32 v73, 0xbfb8aa3b, v73
	v_mul_f32_e32 v81, v74, v81
	v_exp_f32_e32 v72, v72
	v_exp_f32_e32 v73, v73
	v_fma_f32 v81, v74, v81, v74
	v_mul_f32_e32 v81, 0x3f4c422a, v81
	v_add_f32_e32 v81, v81, v81
	v_mul_f32_e32 v81, 0xbfb8aa3b, v81
	v_add_f32_e32 v72, 1.0, v72
	v_add_f32_e32 v73, 1.0, v73
	v_exp_f32_e32 v81, v81
	v_rcp_f32_e32 v72, v72
	v_rcp_f32_e32 v73, v73
	v_pk_mul_f32 v[76:77], v[76:77], v[86:87]
	v_add_f32_e32 v81, 1.0, v81
	v_rcp_f32_e32 v90, v81
	v_mul_f32_e32 v81, 0x3d372713, v79
	v_pk_mul_f32 v[84:85], v[84:85], v[72:73]
	v_mul_f32_e32 v72, 0x3d372713, v75
	v_mul_f32_e32 v81, v79, v81
	v_mul_f32_e32 v72, v75, v72
	v_fma_f32 v81, v79, v81, v79
	v_fma_f32 v72, v75, v72, v75
	v_mul_f32_e32 v81, 0x3f4c422a, v81
	v_mul_f32_e32 v72, 0x3f4c422a, v72
	v_add_f32_e32 v81, v81, v81
	v_add_f32_e32 v72, v72, v72
	v_mul_f32_e32 v81, 0xbfb8aa3b, v81
	v_mul_f32_e32 v72, 0xbfb8aa3b, v72
	v_exp_f32_e32 v81, v81
	v_exp_f32_e32 v72, v72
	v_add_f32_e32 v81, 1.0, v81
	v_add_f32_e32 v72, 1.0, v72
	v_rcp_f32_e32 v89, v81
	v_rcp_f32_e32 v91, v72
	v_pk_mul_f32 v[78:79], v[78:79], v[88:89]
	v_pk_mul_f32 v[74:75], v[74:75], v[90:91]

.LBB0_944:
	v_cvt_pk_bf16_f32 v68, v68, v69
	v_cvt_pk_bf16_f32 v69, v70, v71
	v_cvt_pk_bf16_f32 v70, v64, v65
	v_cvt_pk_bf16_f32 v71, v66, v67
	global_store_dwordx4 v[72:73], v[68:71], off offset:256
	v_mov_b32_e32 v64, v163
	s_and_b64 vcc, exec, s[12:13]
	v_fmamk_f32 v64, v64, 0x3a800000, v227
	v_mul_f32_e32 v65, 0x4b800000, v64
	v_cmp_gt_f32_e64 s[16:17], s2, v64
	s_nop 1
	v_cndmask_b32_e64 v64, v64, v65, s[16:17]
	v_rsq_f32_e32 v64, v64
	s_nop 0
	v_mul_f32_e32 v65, 0x45800000, v64
	v_cndmask_b32_e64 v64, v64, v65, s[16:17]
	v_pk_mul_f32 v[62:63], v[62:63], v[64:65] op_sel_hi:[1,0]
	v_pk_mul_f32 v[66:67], v[60:61], v[64:65] op_sel_hi:[1,0]
	v_pk_mul_f32 v[58:59], v[58:59], v[64:65] op_sel_hi:[1,0]
	v_pk_mul_f32 v[60:61], v[56:57], v[64:65] op_sel_hi:[1,0]
	s_cbranch_vccnz .LBB0_946
	v_mul_f32_e32 v57, 0x3d372713, v60
	v_mul_f32_e32 v57, v60, v57
	v_fma_f32 v57, v60, v57, v60
	v_mul_f32_e32 v57, 0x3f4c422a, v57
	v_add_f32_e32 v57, v57, v57
	v_mul_f32_e32 v57, 0xbfb8aa3b, v57
	v_exp_f32_e32 v57, v57
	v_mov_b32_e32 v65, v67
	v_mov_b32_e32 v69, v61
	v_mul_f32_e32 v56, 0x3d372713, v66
	v_add_f32_e32 v57, 1.0, v57
	v_rcp_f32_e32 v68, v57
	v_mul_f32_e32 v57, 0x3d372713, v67
	v_mul_f32_e32 v57, v67, v57
	v_fmac_f32_e32 v65, v65, v57
	v_mul_f32_e32 v57, 0x3f4c422a, v65
	v_mul_f32_e32 v65, 0x3d372713, v61
	v_mul_f32_e32 v65, v61, v65
	v_fmac_f32_e32 v69, v69, v65
	v_mul_f32_e32 v65, 0x3f4c422a, v69
	v_add_f32_e32 v65, v65, v65
	v_mul_f32_e32 v65, 0xbfb8aa3b, v65
	v_exp_f32_e32 v65, v65
	v_mul_f32_e32 v56, v66, v56
	v_fma_f32 v56, v66, v56, v66
	v_mul_f32_e32 v56, 0x3f4c422a, v56
	v_add_f32_e32 v65, 1.0, v65
	v_rcp_f32_e32 v69, v65
	v_mul_f32_e32 v65, 0x3d372713, v62
	v_mul_f32_e32 v65, v62, v65
	v_fma_f32 v65, v62, v65, v62
	v_mul_f32_e32 v65, 0x3f4c422a, v65
	v_add_f32_e32 v65, v65, v65
	v_mul_f32_e32 v65, 0xbfb8aa3b, v65
	v_exp_f32_e32 v65, v65
	v_add_f32_e32 v56, v56, v56
	v_add_f32_e32 v57, v57, v57
	v_mul_f32_e32 v56, 0xbfb8aa3b, v56
	v_add_f32_e32 v65, 1.0, v65
	v_rcp_f32_e32 v70, v65
	v_mul_f32_e32 v65, 0x3d372713, v58
	v_mul_f32_e32 v57, 0xbfb8aa3b, v57
	v_mul_f32_e32 v65, v58, v65
	v_exp_f32_e32 v56, v56
	v_exp_f32_e32 v57, v57
	v_fma_f32 v65, v58, v65, v58
	v_mul_f32_e32 v65, 0x3f4c422a, v65
	v_add_f32_e32 v65, v65, v65
	v_mul_f32_e32 v65, 0xbfb8aa3b, v65
	v_add_f32_e32 v56, 1.0, v56
	v_add_f32_e32 v57, 1.0, v57
	v_exp_f32_e32 v65, v65
	v_rcp_f32_e32 v56, v56
	v_rcp_f32_e32 v57, v57
	v_pk_mul_f32 v[60:61], v[60:61], v[68:69]
	v_add_f32_e32 v65, 1.0, v65
	v_rcp_f32_e32 v72, v65
	v_mul_f32_e32 v65, 0x3d372713, v63
	v_pk_mul_f32 v[66:67], v[66:67], v[56:57]
	v_mul_f32_e32 v56, 0x3d372713, v59
	v_mul_f32_e32 v65, v63, v65
	v_mul_f32_e32 v56, v59, v56
	v_fma_f32 v65, v63, v65, v63
	v_fma_f32 v56, v59, v56, v59
	v_mul_f32_e32 v65, 0x3f4c422a, v65
	v_mul_f32_e32 v56, 0x3f4c422a, v56
	v_add_f32_e32 v65, v65, v65
	v_add_f32_e32 v56, v56, v56
	v_mul_f32_e32 v65, 0xbfb8aa3b, v65
	v_mul_f32_e32 v56, 0xbfb8aa3b, v56
	v_exp_f32_e32 v65, v65
	v_exp_f32_e32 v56, v56
	v_add_f32_e32 v65, 1.0, v65
	v_add_f32_e32 v56, 1.0, v56
	v_rcp_f32_e32 v71, v65
	v_rcp_f32_e32 v73, v56
	v_pk_mul_f32 v[62:63], v[62:63], v[70:71]
	v_pk_mul_f32 v[58:59], v[58:59], v[72:73]

.LBB0_948:
	v_cvt_pk_bf16_f32 v52, v52, v53
	v_cvt_pk_bf16_f32 v53, v54, v55
	v_cvt_pk_bf16_f32 v54, v48, v49
	v_cvt_pk_bf16_f32 v55, v50, v51
	global_store_dwordx4 v[56:57], v[52:55], off offset:256
	v_mov_b32_e32 v48, v164
	s_and_b64 vcc, exec, s[12:13]
	v_fmamk_f32 v48, v48, 0x3a800000, v227
	v_mul_f32_e32 v49, 0x4b800000, v48
	v_cmp_gt_f32_e64 s[16:17], s2, v48
	s_nop 1
	v_cndmask_b32_e64 v48, v48, v49, s[16:17]
	v_rsq_f32_e32 v48, v48
	s_nop 0
	v_mul_f32_e32 v49, 0x45800000, v48
	v_cndmask_b32_e64 v48, v48, v49, s[16:17]
	v_pk_mul_f32 v[46:47], v[46:47], v[48:49] op_sel_hi:[1,0]
	v_pk_mul_f32 v[50:51], v[44:45], v[48:49] op_sel_hi:[1,0]
	v_pk_mul_f32 v[42:43], v[42:43], v[48:49] op_sel_hi:[1,0]
	v_pk_mul_f32 v[44:45], v[40:41], v[48:49] op_sel_hi:[1,0]
	s_cbranch_vccnz .LBB0_950
	v_mul_f32_e32 v41, 0x3d372713, v44
	v_mul_f32_e32 v41, v44, v41
	v_fma_f32 v41, v44, v41, v44
	v_mul_f32_e32 v41, 0x3f4c422a, v41
	v_add_f32_e32 v41, v41, v41
	v_mul_f32_e32 v41, 0xbfb8aa3b, v41
	v_exp_f32_e32 v41, v41
	v_mov_b32_e32 v49, v51
	v_mov_b32_e32 v53, v45
	v_mul_f32_e32 v40, 0x3d372713, v50
	v_add_f32_e32 v41, 1.0, v41
	v_rcp_f32_e32 v52, v41
	v_mul_f32_e32 v41, 0x3d372713, v51
	v_mul_f32_e32 v41, v51, v41
	v_fmac_f32_e32 v49, v49, v41
	v_mul_f32_e32 v41, 0x3f4c422a, v49
	v_mul_f32_e32 v49, 0x3d372713, v45
	v_mul_f32_e32 v49, v45, v49
	v_fmac_f32_e32 v53, v53, v49
	v_mul_f32_e32 v49, 0x3f4c422a, v53
	v_add_f32_e32 v49, v49, v49
	v_mul_f32_e32 v49, 0xbfb8aa3b, v49
	v_exp_f32_e32 v49, v49
	v_mul_f32_e32 v40, v50, v40
	v_fma_f32 v40, v50, v40, v50
	v_mul_f32_e32 v40, 0x3f4c422a, v40
	v_add_f32_e32 v49, 1.0, v49
	v_rcp_f32_e32 v53, v49
	v_mul_f32_e32 v49, 0x3d372713, v46
	v_mul_f32_e32 v49, v46, v49
	v_fma_f32 v49, v46, v49, v46
	v_mul_f32_e32 v49, 0x3f4c422a, v49
	v_add_f32_e32 v49, v49, v49
	v_mul_f32_e32 v49, 0xbfb8aa3b, v49
	v_exp_f32_e32 v49, v49
	v_add_f32_e32 v40, v40, v40
	v_add_f32_e32 v41, v41, v41
	v_mul_f32_e32 v40, 0xbfb8aa3b, v40
	v_add_f32_e32 v49, 1.0, v49
	v_rcp_f32_e32 v54, v49
	v_mul_f32_e32 v49, 0x3d372713, v42
	v_mul_f32_e32 v41, 0xbfb8aa3b, v41
	v_mul_f32_e32 v49, v42, v49
	v_exp_f32_e32 v40, v40
	v_exp_f32_e32 v41, v41
	v_fma_f32 v49, v42, v49, v42
	v_mul_f32_e32 v49, 0x3f4c422a, v49
	v_add_f32_e32 v49, v49, v49
	v_mul_f32_e32 v49, 0xbfb8aa3b, v49
	v_add_f32_e32 v40, 1.0, v40
	v_add_f32_e32 v41, 1.0, v41
	v_exp_f32_e32 v49, v49
	v_rcp_f32_e32 v40, v40
	v_rcp_f32_e32 v41, v41
	v_pk_mul_f32 v[44:45], v[44:45], v[52:53]
	v_add_f32_e32 v49, 1.0, v49
	v_rcp_f32_e32 v56, v49
	v_mul_f32_e32 v49, 0x3d372713, v47
	v_pk_mul_f32 v[50:51], v[50:51], v[40:41]
	v_mul_f32_e32 v40, 0x3d372713, v43
	v_mul_f32_e32 v49, v47, v49
	v_mul_f32_e32 v40, v43, v40
	v_fma_f32 v49, v47, v49, v47
	v_fma_f32 v40, v43, v40, v43
	v_mul_f32_e32 v49, 0x3f4c422a, v49
	v_mul_f32_e32 v40, 0x3f4c422a, v40
	v_add_f32_e32 v49, v49, v49
	v_add_f32_e32 v40, v40, v40
	v_mul_f32_e32 v49, 0xbfb8aa3b, v49
	v_mul_f32_e32 v40, 0xbfb8aa3b, v40
	v_exp_f32_e32 v49, v49
	v_exp_f32_e32 v40, v40
	v_add_f32_e32 v49, 1.0, v49
	v_add_f32_e32 v40, 1.0, v40
	v_rcp_f32_e32 v55, v49
	v_rcp_f32_e32 v57, v40
	v_pk_mul_f32 v[46:47], v[46:47], v[54:55]
	v_pk_mul_f32 v[42:43], v[42:43], v[56:57]

.LBB0_952:
	v_cvt_pk_bf16_f32 v36, v36, v37
	v_cvt_pk_bf16_f32 v37, v38, v39
	v_cvt_pk_bf16_f32 v38, v32, v33
	v_cvt_pk_bf16_f32 v39, v34, v35
	global_store_dwordx4 v[40:41], v[36:39], off offset:256
	v_mov_b32_e32 v32, v165
	s_and_b64 vcc, exec, s[12:13]
	v_fmamk_f32 v32, v32, 0x3a800000, v227
	v_mul_f32_e32 v33, 0x4b800000, v32
	v_cmp_gt_f32_e64 s[16:17], s2, v32
	s_nop 1
	v_cndmask_b32_e64 v32, v32, v33, s[16:17]
	v_rsq_f32_e32 v32, v32
	s_nop 0
	v_mul_f32_e32 v33, 0x45800000, v32
	v_cndmask_b32_e64 v32, v32, v33, s[16:17]
	v_pk_mul_f32 v[30:31], v[30:31], v[32:33] op_sel_hi:[1,0]
	v_pk_mul_f32 v[34:35], v[28:29], v[32:33] op_sel_hi:[1,0]
	v_pk_mul_f32 v[26:27], v[26:27], v[32:33] op_sel_hi:[1,0]
	v_pk_mul_f32 v[28:29], v[24:25], v[32:33] op_sel_hi:[1,0]
	s_cbranch_vccnz .LBB0_954
	v_mul_f32_e32 v25, 0x3d372713, v28
	v_mul_f32_e32 v25, v28, v25
	v_fma_f32 v25, v28, v25, v28
	v_mul_f32_e32 v25, 0x3f4c422a, v25
	v_add_f32_e32 v25, v25, v25
	v_mul_f32_e32 v25, 0xbfb8aa3b, v25
	v_exp_f32_e32 v25, v25
	v_mov_b32_e32 v33, v35
	v_mov_b32_e32 v37, v29
	v_mul_f32_e32 v24, 0x3d372713, v34
	v_add_f32_e32 v25, 1.0, v25
	v_rcp_f32_e32 v36, v25
	v_mul_f32_e32 v25, 0x3d372713, v35
	v_mul_f32_e32 v25, v35, v25
	v_fmac_f32_e32 v33, v33, v25
	v_mul_f32_e32 v25, 0x3f4c422a, v33
	v_mul_f32_e32 v33, 0x3d372713, v29
	v_mul_f32_e32 v33, v29, v33
	v_fmac_f32_e32 v37, v37, v33
	v_mul_f32_e32 v33, 0x3f4c422a, v37
	v_add_f32_e32 v33, v33, v33
	v_mul_f32_e32 v33, 0xbfb8aa3b, v33
	v_exp_f32_e32 v33, v33
	v_mul_f32_e32 v24, v34, v24
	v_fma_f32 v24, v34, v24, v34
	v_mul_f32_e32 v24, 0x3f4c422a, v24
	v_add_f32_e32 v33, 1.0, v33
	v_rcp_f32_e32 v37, v33
	v_mul_f32_e32 v33, 0x3d372713, v30
	v_mul_f32_e32 v33, v30, v33
	v_fma_f32 v33, v30, v33, v30
	v_mul_f32_e32 v33, 0x3f4c422a, v33
	v_add_f32_e32 v33, v33, v33
	v_mul_f32_e32 v33, 0xbfb8aa3b, v33
	v_exp_f32_e32 v33, v33
	v_add_f32_e32 v24, v24, v24
	v_add_f32_e32 v25, v25, v25
	v_mul_f32_e32 v24, 0xbfb8aa3b, v24
	v_add_f32_e32 v33, 1.0, v33
	v_rcp_f32_e32 v38, v33
	v_mul_f32_e32 v33, 0x3d372713, v26
	v_mul_f32_e32 v25, 0xbfb8aa3b, v25
	v_mul_f32_e32 v33, v26, v33
	v_exp_f32_e32 v24, v24
	v_exp_f32_e32 v25, v25
	v_fma_f32 v33, v26, v33, v26
	v_mul_f32_e32 v33, 0x3f4c422a, v33
	v_add_f32_e32 v33, v33, v33
	v_mul_f32_e32 v33, 0xbfb8aa3b, v33
	v_add_f32_e32 v24, 1.0, v24
	v_add_f32_e32 v25, 1.0, v25
	v_exp_f32_e32 v33, v33
	v_rcp_f32_e32 v24, v24
	v_rcp_f32_e32 v25, v25
	v_pk_mul_f32 v[28:29], v[28:29], v[36:37]
	v_add_f32_e32 v33, 1.0, v33
	v_rcp_f32_e32 v40, v33
	v_mul_f32_e32 v33, 0x3d372713, v31
	v_pk_mul_f32 v[34:35], v[34:35], v[24:25]
	v_mul_f32_e32 v24, 0x3d372713, v27
	v_mul_f32_e32 v33, v31, v33
	v_mul_f32_e32 v24, v27, v24
	v_fma_f32 v33, v31, v33, v31
	v_fma_f32 v24, v27, v24, v27
	v_mul_f32_e32 v33, 0x3f4c422a, v33
	v_mul_f32_e32 v24, 0x3f4c422a, v24
	v_add_f32_e32 v33, v33, v33
	v_add_f32_e32 v24, v24, v24
	v_mul_f32_e32 v33, 0xbfb8aa3b, v33
	v_mul_f32_e32 v24, 0xbfb8aa3b, v24
	v_exp_f32_e32 v33, v33
	v_exp_f32_e32 v24, v24
	v_add_f32_e32 v33, 1.0, v33
	v_add_f32_e32 v24, 1.0, v24
	v_rcp_f32_e32 v39, v33
	v_rcp_f32_e32 v41, v24
	v_pk_mul_f32 v[30:31], v[30:31], v[38:39]
	v_pk_mul_f32 v[26:27], v[26:27], v[40:41]

.LBB0_956:
	v_cvt_pk_bf16_f32 v20, v20, v21
	v_cvt_pk_bf16_f32 v21, v22, v23
	v_cvt_pk_bf16_f32 v22, v16, v17
	v_cvt_pk_bf16_f32 v23, v18, v19
	global_store_dwordx4 v[24:25], v[20:23], off offset:256
	v_mov_b32_e32 v16, v166
	s_and_b64 vcc, exec, s[12:13]
	v_fmamk_f32 v16, v16, 0x3a800000, v227
	v_mul_f32_e32 v17, 0x4b800000, v16
	v_cmp_gt_f32_e64 s[16:17], s2, v16
	s_nop 1
	v_cndmask_b32_e64 v16, v16, v17, s[16:17]
	v_rsq_f32_e32 v16, v16
	s_nop 0
	v_mul_f32_e32 v17, 0x45800000, v16
	v_cndmask_b32_e64 v16, v16, v17, s[16:17]
	v_pk_mul_f32 v[14:15], v[14:15], v[16:17] op_sel_hi:[1,0]
	v_pk_mul_f32 v[18:19], v[12:13], v[16:17] op_sel_hi:[1,0]
	v_pk_mul_f32 v[10:11], v[10:11], v[16:17] op_sel_hi:[1,0]
	v_pk_mul_f32 v[12:13], v[8:9], v[16:17] op_sel_hi:[1,0]
	s_cbranch_vccnz .LBB0_958
	v_mul_f32_e32 v9, 0x3d372713, v12
	v_mul_f32_e32 v9, v12, v9
	v_fma_f32 v9, v12, v9, v12
	v_mul_f32_e32 v9, 0x3f4c422a, v9
	v_add_f32_e32 v9, v9, v9
	v_mul_f32_e32 v9, 0xbfb8aa3b, v9
	v_exp_f32_e32 v9, v9
	v_mov_b32_e32 v17, v19
	v_mov_b32_e32 v21, v13
	v_mul_f32_e32 v8, 0x3d372713, v18
	v_add_f32_e32 v9, 1.0, v9
	v_rcp_f32_e32 v20, v9
	v_mul_f32_e32 v9, 0x3d372713, v19
	v_mul_f32_e32 v9, v19, v9
	v_fmac_f32_e32 v17, v17, v9
	v_mul_f32_e32 v9, 0x3f4c422a, v17
	v_mul_f32_e32 v17, 0x3d372713, v13
	v_mul_f32_e32 v17, v13, v17
	v_fmac_f32_e32 v21, v21, v17
	v_mul_f32_e32 v17, 0x3f4c422a, v21
	v_add_f32_e32 v17, v17, v17
	v_mul_f32_e32 v17, 0xbfb8aa3b, v17
	v_exp_f32_e32 v17, v17
	v_mul_f32_e32 v8, v18, v8
	v_fma_f32 v8, v18, v8, v18
	v_mul_f32_e32 v8, 0x3f4c422a, v8
	v_add_f32_e32 v17, 1.0, v17
	v_rcp_f32_e32 v21, v17
	v_mul_f32_e32 v17, 0x3d372713, v14
	v_mul_f32_e32 v17, v14, v17
	v_fma_f32 v17, v14, v17, v14
	v_mul_f32_e32 v17, 0x3f4c422a, v17
	v_add_f32_e32 v17, v17, v17
	v_mul_f32_e32 v17, 0xbfb8aa3b, v17
	v_exp_f32_e32 v17, v17
	v_add_f32_e32 v8, v8, v8
	v_add_f32_e32 v9, v9, v9
	v_mul_f32_e32 v8, 0xbfb8aa3b, v8
	v_add_f32_e32 v17, 1.0, v17
	v_rcp_f32_e32 v22, v17
	v_mul_f32_e32 v17, 0x3d372713, v10
	v_mul_f32_e32 v9, 0xbfb8aa3b, v9
	v_mul_f32_e32 v17, v10, v17
	v_exp_f32_e32 v8, v8
	v_exp_f32_e32 v9, v9
	v_fma_f32 v17, v10, v17, v10
	v_mul_f32_e32 v17, 0x3f4c422a, v17
	v_add_f32_e32 v17, v17, v17
	v_mul_f32_e32 v17, 0xbfb8aa3b, v17
	v_add_f32_e32 v8, 1.0, v8
	v_add_f32_e32 v9, 1.0, v9
	v_exp_f32_e32 v17, v17
	v_rcp_f32_e32 v8, v8
	v_rcp_f32_e32 v9, v9
	v_pk_mul_f32 v[12:13], v[12:13], v[20:21]
	v_add_f32_e32 v17, 1.0, v17
	v_rcp_f32_e32 v24, v17
	v_mul_f32_e32 v17, 0x3d372713, v15
	v_pk_mul_f32 v[18:19], v[18:19], v[8:9]
	v_mul_f32_e32 v8, 0x3d372713, v11
	v_mul_f32_e32 v17, v15, v17
	v_mul_f32_e32 v8, v11, v8
	v_fma_f32 v17, v15, v17, v15
	v_fma_f32 v8, v11, v8, v11
	v_mul_f32_e32 v17, 0x3f4c422a, v17
	v_mul_f32_e32 v8, 0x3f4c422a, v8
	v_add_f32_e32 v17, v17, v17
	v_add_f32_e32 v8, v8, v8
	v_mul_f32_e32 v17, 0xbfb8aa3b, v17
	v_mul_f32_e32 v8, 0xbfb8aa3b, v8
	v_exp_f32_e32 v17, v17
	v_exp_f32_e32 v8, v8
	v_add_f32_e32 v17, 1.0, v17
	v_add_f32_e32 v8, 1.0, v8
	v_rcp_f32_e32 v23, v17
	v_rcp_f32_e32 v25, v8
	v_pk_mul_f32 v[14:15], v[14:15], v[22:23]
	v_pk_mul_f32 v[10:11], v[10:11], v[24:25]
